# windowed-attention prologue: bias-table loads de-serialised (5/8 loads issued together, one wait) on top of v36
# baseline (speedup 1.0000x reference)
; #define SA_LOAD(tbase) do { const bf16* kp_ = Kp + (size_t)((tbase) + r32) * kvpitch + 8 * hi; \
;         _Pragma("unroll") for (int ks = 0; ks < 4; ++ks) kf[ks] = *(const bf16x8*)(kp_ + 16 * ks); \
;         _Pragma("unroll") for (int e = 0; e < 4; ++e) { const int c = lane + 64 * e; vr[e] = *(const v4u*)(Vp + (size_t)((tbase) + (c >> 3)) * kvpitch + (c & 7) * 8); } } while (0)
; template <int MODE> ...
;     ...
;     const int qrow = qt + (r32 >> 4), qc = qcol0 + (r32 & 15);
;     const int qtok = MODE == 0 ? qt + r32 : qrow * 64 + qc;
;     bf16x8 qf[4];
; #pragma unroll
;     for (int ks = 0; ks < 4; ++ks) qf[ks] = *(const bf16x8*)(Qb + (size_t)qtok * qpitch + 16 * ks + 8 * hi);
;     int nt, tb0, tstep, rsA = 0, kc0 = 0, my_rs = 0, my_cs = 0;
;     if (MODE == 0) { const int t0 = qt - 128 < 0 ? 0 : qt - 128; const int t1 = qt + 160 > SEQ_ ? SEQ_ : qt + 160; tb0 = t0; nt = (t1 - t0) >> 5; tstep = 32; }
;     else { rsA = qt - 4; rsA = rsA < 0 ? 0 : (rsA > 248 ? 248 : rsA); int rsB = qt - 3; rsB = rsB < 0 ? 0 : (rsB > 248 ? 248 : rsB); nt = 8 + (rsB - rsA);
;         kc0 = qcol0 - 8; kc0 = kc0 < 0 ? 0 : (kc0 > 32 ? 32 : kc0); tb0 = rsA * 64 + kc0; tstep = 64;
;         my_rs = qrow - 4; my_rs = my_rs < 0 ? 0 : (my_rs > 248 ? 248 : my_rs); my_cs = qc - 8; my_cs = my_cs < 0 ? 0 : (my_cs > 48 ? 48 : my_cs); }
;     bf16x8 kf[4]; v4u vr[4];
;     ...
;     SA_LOAD(tb0);
;     float bmx = -1e30f;
;     for (int e = lane; e < ntab; e += 64) { const float tv_ = gtab[e] * tabscale; tab[e] = tv_; bmx = fmaxf(bmx, tv_); }
; #pragma unroll
;     for (int o_ = 1; o_ < 64; o_ <<= 1) bmx = fmaxf(bmx, __shfl_xor(bmx, o_));
; __global__ void __launch_bounds__(512) mega_fwd(Args args) {
;     ...
;                 const int u = uu % 768; const int qb = u & 63, h = (u >> 6) % 6, b = u / 384; const int qt = qb * 256 + wave * 32; const size_t rb = (size_t)b * SEQ_;
;                 small_attn_wave<0>(QKV + pg8::OFF_QB + rb * 384 + h * 64, 384, QKV + pg8::OFF_KB + rb * 128 + (h / 3) * 64, QKV + pg8::OFF_VB + rb * 128 + (h / 3) * 64, 128,
;                                    YB + rb * 1024 + 256 + h * 64, qt, 0, (const float*)(ws + WS_SWB) + h * 260, 257, 1.0f, args.in[I_SINK][l * 6 + h] * LOG2E_, GSS + (size_t)(l * 3 + 1) * MT + rb, (const unsigned*)(ws + WS_KMAX) + ((l * 2 + 1) * 4 + h / 3) * 2, wl, lane);
.LBB0_464:
	s_mul_hi_i32 s0, s29, 0x2aaaaaab
	s_lshr_b32 s1, s0, 31
	s_lshr_b32 s0, s0, 7
	s_add_i32 s0, s0, s1
	s_mulk_i32 s0, 0x300
	s_sub_i32 s4, s29, s0
	s_lshr_b32 s0, s4, 6
	s_bfe_i32 s1, s0, 0x80000
	s_mul_i32 s1, s1, 43
	s_bfe_u32 s5, s1, 0x1000f
	s_bfe_u32 s1, s1, 0x80008
	s_add_i32 s1, s1, s5
	s_mul_i32 s1, s1, 6
	s_sub_i32 s30, s0, s1
	s_mul_i32 s0, s4, 0x2aab
	s_lshr_b32 s1, s0, 31
	s_ashr_i32 s0, s0, 22
	s_add_i32 s40, s0, s1
	s_lshl_b32 s0, s4, 8
	s_and_b32 s5, s0, 0x3f00
	s_add_i32 s31, s5, s11
	s_ashr_i32 s41, s40, 31
	s_mul_i32 s1, s40, 0xc00000
	v_readlane_b32 s12, v254, 3
	s_sext_i32_i8 s37, s30
	s_mul_hi_i32 s0, s40, 0xc00000
	s_add_u32 s34, s12, s1
	v_readlane_b32 s1, v254, 4
	s_addc_u32 s44, s1, s0
	s_lshl_b32 s0, s37, 6
	s_ashr_i32 s1, s0, 31
	s_lshl_b64 s[42:43], s[0:1], 1
	s_add_u32 s0, s34, s42
	s_addc_u32 s1, s44, s43
	s_lshl_b64 s[46:47], s[40:41], 22
	v_readlane_b32 s12, v254, 5
	s_add_u32 s50, s12, s46
	v_readlane_b32 s12, v254, 6
	s_addc_u32 s51, s12, s47
	s_bfe_i32 s30, s30, 0x80000
	s_mulk_i32 s30, 0x56
	s_bfe_u32 s34, s30, 0x1000f
	s_bfe_u32 s30, s30, 0x80008
	s_add_i32 s30, s30, s34
	s_sext_i32_i8 s34, s30
	s_lshl_b32 s44, s34, 6
	s_ashr_i32 s45, s44, 31
	s_lshl_b64 s[48:49], s[44:45], 1
	s_add_u32 s44, s50, s48
	s_addc_u32 s45, s51, s49
	v_readlane_b32 s12, v254, 7
	s_add_u32 s30, s12, s46
	v_readlane_b32 s12, v254, 8
	s_addc_u32 s47, s12, s47
	s_add_u32 s46, s30, s48
	s_mul_i32 s30, s60, 6
	s_addc_u32 s47, s47, s49
	s_add_i32 s50, s30, s37
	s_mul_i32 s48, s37, 0x104
	s_ashr_i32 s51, s50, 31
	s_ashr_i32 s49, s48, 31
	s_lshl_b64 s[50:51], s[50:51], 2
	s_add_u32 s50, s58, s50
	v_or_b32_e32 v124, s31, v113
	v_mov_b64_e32 v[0:1], s[0:1]
	s_movk_i32 s0, 0x300
	s_addc_u32 s51, s59, s51
	v_mad_i64_i32 v[0:1], s[0:1], v124, s0, v[0:1]
	v_lshlrev_b32_e32 v128, 1, v112
	s_max_i32 s30, s31, 0x80
	v_lshl_add_u64 v[0:1], v[0:1], 0, v[128:129]
	s_add_i32 s37, s30, 0xffffff80
	global_load_dword v168, v129, s[50:51]
	global_load_dwordx4 v[64:67], v[0:1], off
	global_load_dwordx4 v[68:71], v[0:1], off offset:32
	global_load_dwordx4 v[72:75], v[0:1], off offset:64
	global_load_dwordx4 v[76:79], v[0:1], off offset:96
	v_or_b32_e32 v0, s37, v113
	v_mov_b32_e32 v1, v129
	v_lshlrev_b64 v[0:1], 8, v[0:1]
	v_lshl_add_u64 v[0:1], s[44:45], 0, v[0:1]
	v_lshl_add_u64 v[0:1], v[0:1], 0, v[128:129]
	global_load_dwordx4 v[80:83], v[0:1], off
	global_load_dwordx4 v[84:87], v[0:1], off offset:32
	global_load_dwordx4 v[88:91], v[0:1], off offset:64
	global_load_dwordx4 v[92:95], v[0:1], off offset:96
	v_mov_b32_e32 v123, v129
	v_or_b32_e32 v0, s37, v150
	v_mov_b32_e32 v1, v129
	v_lshl_add_u64 v[126:127], s[46:47], 0, v[122:123]
	v_lshlrev_b64 v[0:1], 8, v[0:1]
	v_or_b32_e32 v2, s37, v151
	v_mov_b32_e32 v3, v129
	v_lshl_add_u64 v[0:1], v[126:127], 0, v[0:1]
	v_lshlrev_b64 v[2:3], 8, v[2:3]
	v_lshl_add_u64 v[2:3], v[126:127], 0, v[2:3]
	global_load_dwordx4 v[96:99], v[0:1], off
	global_load_dwordx4 v[100:103], v[2:3], off
	v_or_b32_e32 v0, s37, v152
	v_mov_b32_e32 v1, v129
	v_lshlrev_b64 v[0:1], 8, v[0:1]
	v_or_b32_e32 v2, s37, v153
	v_mov_b32_e32 v3, v129
	v_lshl_add_u64 v[0:1], v[126:127], 0, v[0:1]
	v_lshlrev_b64 v[2:3], 8, v[2:3]
	v_lshl_add_u64 v[2:3], v[126:127], 0, v[2:3]
	global_load_dwordx4 v[104:107], v[0:1], off
	global_load_dwordx4 v[108:111], v[2:3], off
	v_ashrrev_i32_e32 v125, 31, v124
	v_lshl_add_u64 v[0:1], s[48:49], 2, v[120:121]
	v_mov_b32_e32 v2, 0xf149f2ca
	s_movk_i32 s46, 0xc0
	global_load_dword v5, v[0:1], off
	global_load_dword v6, v[0:1], off offset:256
	global_load_dword v7, v[0:1], off offset:512
	global_load_dword v8, v[0:1], off offset:768
	s_mov_b64 s[0:1], exec
	v_cmp_eq_u32_e32 vcc, 0, v133
	s_and_b64 exec, exec, vcc
	global_load_dword v9, v[0:1], off offset:1024
	s_mov_b64 exec, s[0:1]
	s_waitcnt vmcnt(0)
	ds_write_b32 v164, v5
	ds_write_b32 v164, v6 offset:256
	ds_write_b32 v164, v7 offset:512
	ds_write_b32 v164, v8 offset:768
	v_max_f32_e32 v5, v5, v5
	v_max_f32_e32 v6, v6, v6
	v_max_f32_e32 v7, v7, v7
	v_max_f32_e32 v8, v8, v8
	v_max_f32_e32 v2, v2, v5
	v_max_f32_e32 v2, v2, v6
	v_max_f32_e32 v2, v2, v7
	v_max_f32_e32 v2, v2, v8
	s_and_b64 exec, exec, vcc
	ds_write_b32 v164, v9 offset:1024
	v_max_f32_e32 v9, v9, v9
	v_max_f32_e32 v2, v2, v9
	s_mov_b64 exec, s[0:1]
	s_add_i32 s0, s20, s34
	s_lshl_b32 s34, s0, 1
	s_lshl_b64 s[0:1], s[34:35], 2
	ds_bpermute_b32 v0, v137, v2
	s_add_u32 s0, s76, s0
	s_addc_u32 s1, s77, s1
	global_load_dwordx2 v[16:17], v129, s[0:1]
	v_max_f32_e32 v1, v2, v2
	s_waitcnt lgkmcnt(0)
	v_max_f32_e32 v0, v0, v0
	v_max_f32_e32 v0, v1, v0
	ds_bpermute_b32 v1, v138, v0
	v_and_b32_e32 v2, 0xffff0000, v65
	v_mul_f32_e32 v2, v2, v2
	s_sub_i32 s0, s30, s31
	s_sub_i32 s34, s0, 32
	s_waitcnt lgkmcnt(0)
	v_max_f32_e32 v1, v1, v1
	v_max_f32_e32 v0, v0, v1
	ds_bpermute_b32 v1, v139, v0
	s_mov_b64 s[0:1], -1
	s_cmpk_gt_u32 s34, 0xc0
	ds_write_b128 v166, v[96:99]
	ds_write_b128 v166, v[100:103] offset:1152
	ds_write_b128 v166, v[104:107] offset:2304
	ds_write_b128 v166, v[108:111] offset:3456
	s_waitcnt lgkmcnt(4)
	v_max_f32_e32 v1, v1, v1
	v_max_f32_e32 v0, v0, v1
	ds_bpermute_b32 v1, v140, v0
	s_waitcnt lgkmcnt(0)
	v_max_f32_e32 v1, v1, v1
	v_max_f32_e32 v0, v0, v1
	ds_bpermute_b32 v1, v141, v0
	s_waitcnt lgkmcnt(0)
; #define SA_LOAD(tbase) do { const bf16* kp_ = Kp + (size_t)((tbase) + r32) * kvpitch + 8 * hi; \
;         _Pragma("unroll") for (int ks = 0; ks < 4; ++ks) kf[ks] = *(const bf16x8*)(kp_ + 16 * ks); \
;         _Pragma("unroll") for (int e = 0; e < 4; ++e) { const int c = lane + 64 * e; vr[e] = *(const v4u*)(Vp + (size_t)((tbase) + (c >> 3)) * kvpitch + (c & 7) * 8); } } while (0)
; template <int MODE> ...
;     ...
;     SA_LOAD(tb0);
;     float bmx = -1e30f;
;     for (int e = lane; e < ntab; e += 64) { const float tv_ = gtab[e] * tabscale; tab[e] = tv_; bmx = fmaxf(bmx, tv_); }
; #pragma unroll
;     for (int o_ = 1; o_ < 64; o_ <<= 1) bmx = fmaxf(bmx, __shfl_xor(bmx, o_));
;     float ref;
;     { float qs = 0.f;
; #pragma unroll
;       for (int ks = 0; ks < 4; ++ks) { const v4u qw = __builtin_bit_cast(v4u, qf[ks]);
; #pragma unroll
;           for (int e = 0; e < 4; ++e) { const float lo_ = __uint_as_float(qw[e] << 16), hi_ = __uint_as_float(qw[e] & 0xffff0000u); qs += lo_ * lo_ + hi_ * hi_; } }
;       auto rr = __builtin_amdgcn_permlane32_swap(__float_as_uint(qs), __float_as_uint(qs), false, false); qs = __uint_as_float(rr[0]) + __uint_as_float(rr[1]);
;       const float k2 = __uint_as_float(kmax2[0]) + __uint_as_float(kmax2[1]);
;       ref = fminf(__builtin_sqrtf(qs * k2) * 1.03f + bmx, 110.0f); }
	v_max_f32_e32 v1, v1, v1
	v_max_f32_e32 v18, v0, v1
	v_and_b32_e32 v1, 0xffff0000, v64
	v_lshlrev_b32_e32 v0, 16, v64
	v_mul_f32_e32 v1, v1, v1
	v_fmac_f32_e32 v1, v0, v0
	v_lshlrev_b32_e32 v0, 16, v65
	v_fmac_f32_e32 v2, v0, v0
	v_add_f32_e32 v0, v1, v2
	v_and_b32_e32 v2, 0xffff0000, v66
	v_lshlrev_b32_e32 v1, 16, v66
	v_mul_f32_e32 v2, v2, v2
	v_fmac_f32_e32 v2, v1, v1
	v_add_f32_e32 v0, v2, v0
	v_and_b32_e32 v2, 0xffff0000, v67
	v_lshlrev_b32_e32 v1, 16, v67
	v_mul_f32_e32 v2, v2, v2
	v_fmac_f32_e32 v2, v1, v1
	v_add_f32_e32 v0, v2, v0
	v_and_b32_e32 v2, 0xffff0000, v68
	v_lshlrev_b32_e32 v1, 16, v68
	v_mul_f32_e32 v2, v2, v2
	v_fmac_f32_e32 v2, v1, v1
	v_add_f32_e32 v0, v2, v0
	v_and_b32_e32 v2, 0xffff0000, v69
	v_lshlrev_b32_e32 v1, 16, v69
	v_mul_f32_e32 v2, v2, v2
	v_fmac_f32_e32 v2, v1, v1
	v_add_f32_e32 v0, v2, v0
	v_and_b32_e32 v2, 0xffff0000, v70
	v_lshlrev_b32_e32 v1, 16, v70
	v_mul_f32_e32 v2, v2, v2
	v_fmac_f32_e32 v2, v1, v1
	v_add_f32_e32 v0, v2, v0
	v_and_b32_e32 v2, 0xffff0000, v71
	v_lshlrev_b32_e32 v1, 16, v71
	v_mul_f32_e32 v2, v2, v2
	v_fmac_f32_e32 v2, v1, v1
	v_add_f32_e32 v0, v2, v0
	v_and_b32_e32 v2, 0xffff0000, v72
	v_lshlrev_b32_e32 v1, 16, v72
	v_mul_f32_e32 v2, v2, v2
	v_fmac_f32_e32 v2, v1, v1
	v_add_f32_e32 v0, v2, v0
	v_and_b32_e32 v2, 0xffff0000, v73
	v_lshlrev_b32_e32 v1, 16, v73
	v_mul_f32_e32 v2, v2, v2
	v_fmac_f32_e32 v2, v1, v1
	v_add_f32_e32 v0, v2, v0
	v_and_b32_e32 v2, 0xffff0000, v74
	v_lshlrev_b32_e32 v1, 16, v74
	v_mul_f32_e32 v2, v2, v2
	v_fmac_f32_e32 v2, v1, v1
	v_add_f32_e32 v0, v2, v0
	v_and_b32_e32 v2, 0xffff0000, v75
	v_lshlrev_b32_e32 v1, 16, v75
	v_mul_f32_e32 v2, v2, v2
	v_fmac_f32_e32 v2, v1, v1
	v_add_f32_e32 v0, v2, v0
	v_and_b32_e32 v2, 0xffff0000, v76
	v_lshlrev_b32_e32 v1, 16, v76
	v_mul_f32_e32 v2, v2, v2
	v_fmac_f32_e32 v2, v1, v1
	v_add_f32_e32 v0, v2, v0
	v_and_b32_e32 v2, 0xffff0000, v77
	v_lshlrev_b32_e32 v1, 16, v77
	v_mul_f32_e32 v2, v2, v2
	v_fmac_f32_e32 v2, v1, v1
	v_add_f32_e32 v0, v2, v0
	v_and_b32_e32 v2, 0xffff0000, v78
	v_lshlrev_b32_e32 v1, 16, v78
	v_mul_f32_e32 v2, v2, v2
	v_fmac_f32_e32 v2, v1, v1
	v_add_f32_e32 v0, v2, v0
	v_and_b32_e32 v2, 0xffff0000, v79
	ds_bpermute_b32 v19, v142, v18
	v_lshlrev_b32_e32 v1, 16, v79
	v_mul_f32_e32 v2, v2, v2
	v_fmac_f32_e32 v2, v1, v1
	v_add_f32_e32 v20, v2, v0
	v_mov_b32_e32 v21, v20
	s_nop 1
	v_permlane32_swap_b32_e32 v20, v21
	s_cbranch_scc0 .LBB0_500
	v_sub_u32_e32 v0, s37, v124
	v_add_u32_e32 v22, v0, v116
	v_add_u32_e32 v0, 0x80, v22
	v_cmp_gt_u32_e32 vcc, s33, v0
	v_mov_b32_e32 v1, 0xf149f2ca
	v_mov_b32_e32 v0, 0xf149f2ca
	s_and_saveexec_b64 s[0:1], vcc
	v_sub_u32_e32 v0, s30, v124
	v_add_u32_e32 v0, v0, v143
	v_lshl_add_u32 v0, v0, 2, s8
	ds_read_b32 v0, v0 offset:8704
	s_or_b64 exec, exec, s[0:1]
	v_add_u32_e32 v2, 0x81, v22
	v_cmp_gt_u32_e32 vcc, s33, v2
	s_and_saveexec_b64 s[0:1], vcc
	v_sub_u32_e32 v1, s30, v124
	v_add_u32_e32 v1, v1, v144
	v_lshl_add_u32 v1, v1, 2, s8
	ds_read_b32 v1, v1 offset:8704
	s_or_b64 exec, exec, s[0:1]
	v_add_u32_e32 v2, 0x82, v22
	v_cmp_gt_u32_e32 vcc, s33, v2
	v_mov_b32_e32 v3, 0xf149f2ca
	v_mov_b32_e32 v2, 0xf149f2ca
	s_and_saveexec_b64 s[0:1], vcc
	v_sub_u32_e32 v2, s30, v124
	v_add_u32_e32 v2, v2, v145
	v_lshl_add_u32 v2, v2, 2, s8
	ds_read_b32 v2, v2 offset:8704
	s_or_b64 exec, exec, s[0:1]
	v_add_u32_e32 v4, 0x83, v22
	v_cmp_gt_u32_e32 vcc, s33, v4
	s_and_saveexec_b64 s[0:1], vcc
	v_sub_u32_e32 v3, s30, v124
	v_add_u32_e32 v3, v3, v146
	v_lshl_add_u32 v3, v3, 2, s8
	ds_read_b32 v3, v3 offset:8704
	s_or_b64 exec, exec, s[0:1]
	v_add_u32_e32 v4, 0x88, v22
	v_cmp_gt_u32_e32 vcc, s33, v4
	v_mov_b32_e32 v5, 0xf149f2ca
	v_mov_b32_e32 v4, 0xf149f2ca
	s_and_saveexec_b64 s[0:1], vcc
	v_sub_u32_e32 v4, s30, v124
	v_add_u32_e32 v4, v4, v147
	v_lshl_add_u32 v4, v4, 2, s8
	ds_read_b32 v4, v4 offset:8704
	s_or_b64 exec, exec, s[0:1]
	v_add_u32_e32 v6, 0x89, v22
	v_cmp_gt_u32_e32 vcc, s33, v6
	s_and_saveexec_b64 s[0:1], vcc
	v_sub_u32_e32 v5, s30, v124
	v_add_u32_e32 v5, v5, v148
	v_lshl_add_u32 v5, v5, 2, s8
	ds_read_b32 v5, v5 offset:8704
	s_or_b64 exec, exec, s[0:1]
	v_add_u32_e32 v6, 0x8a, v22
	v_cmp_gt_u32_e32 vcc, s33, v6
	v_mov_b32_e32 v7, 0xf149f2ca
	v_mov_b32_e32 v6, 0xf149f2ca
	s_and_saveexec_b64 s[0:1], vcc
	v_sub_u32_e32 v6, s30, v124
	v_add_u32_e32 v6, v6, v149
	v_lshl_add_u32 v6, v6, 2, s8
	ds_read_b32 v6, v6 offset:8704
	s_or_b64 exec, exec, s[0:1]
	v_add_u32_e32 v8, 0x8b, v22
	v_cmp_gt_u32_e32 vcc, s33, v8
	s_and_saveexec_b64 s[0:1], vcc
	v_sub_u32_e32 v7, s30, v124
	v_add_u32_e32 v7, v7, v155
	v_lshl_add_u32 v7, v7, 2, s8
	ds_read_b32 v7, v7 offset:8704
	s_or_b64 exec, exec, s[0:1]
	v_add_u32_e32 v8, 0x90, v22
	v_cmp_gt_u32_e32 vcc, s33, v8
	v_mov_b32_e32 v9, 0xf149f2ca
	v_mov_b32_e32 v8, 0xf149f2ca
	s_and_saveexec_b64 s[0:1], vcc
	v_sub_u32_e32 v8, s30, v124
	v_add_u32_e32 v8, v8, v156
	v_lshl_add_u32 v8, v8, 2, s8
	ds_read_b32 v8, v8 offset:8704
	s_or_b64 exec, exec, s[0:1]
	v_add_u32_e32 v10, 0x91, v22
	v_cmp_gt_u32_e32 vcc, s33, v10
	s_and_saveexec_b64 s[0:1], vcc
	v_sub_u32_e32 v9, s30, v124
	v_add_u32_e32 v9, v9, v157
	v_lshl_add_u32 v9, v9, 2, s8
	ds_read_b32 v9, v9 offset:8704
	s_or_b64 exec, exec, s[0:1]
	v_add_u32_e32 v10, 0x92, v22
	v_cmp_gt_u32_e32 vcc, s33, v10
	v_mov_b32_e32 v11, 0xf149f2ca
	v_mov_b32_e32 v10, 0xf149f2ca
	s_and_saveexec_b64 s[0:1], vcc
	v_sub_u32_e32 v10, s30, v124
	v_add_u32_e32 v10, v10, v158
	v_lshl_add_u32 v10, v10, 2, s8
	ds_read_b32 v10, v10 offset:8704
	s_or_b64 exec, exec, s[0:1]
	v_add_u32_e32 v12, 0x93, v22
	v_cmp_gt_u32_e32 vcc, s33, v12
	s_and_saveexec_b64 s[0:1], vcc
	v_sub_u32_e32 v11, s30, v124
	v_add_u32_e32 v11, v11, v159
	v_lshl_add_u32 v11, v11, 2, s8
	ds_read_b32 v11, v11 offset:8704
	s_or_b64 exec, exec, s[0:1]
	v_add_u32_e32 v12, 0x98, v22
	v_cmp_gt_u32_e32 vcc, s33, v12
	v_mov_b32_e32 v13, 0xf149f2ca
	v_mov_b32_e32 v12, 0xf149f2ca
	s_and_saveexec_b64 s[0:1], vcc
	v_sub_u32_e32 v12, s30, v124
	v_add_u32_e32 v12, v12, v160
	v_lshl_add_u32 v12, v12, 2, s8
	ds_read_b32 v12, v12 offset:8704
	s_or_b64 exec, exec, s[0:1]
	v_add_u32_e32 v14, 0x99, v22
	v_cmp_gt_u32_e32 vcc, s33, v14
	s_and_saveexec_b64 s[0:1], vcc
	v_sub_u32_e32 v13, s30, v124
	v_add_u32_e32 v13, v13, v161
	v_lshl_add_u32 v13, v13, 2, s8
	ds_read_b32 v13, v13 offset:8704
	s_or_b64 exec, exec, s[0:1]
	v_add_u32_e32 v14, 0x9a, v22
	v_cmp_gt_u32_e32 vcc, s33, v14
	v_mov_b32_e32 v15, 0xf149f2ca
	v_mov_b32_e32 v14, 0xf149f2ca
	s_and_saveexec_b64 s[0:1], vcc
	v_sub_u32_e32 v14, s30, v124
	v_add_u32_e32 v14, v14, v162
	v_lshl_add_u32 v14, v14, 2, s8
	ds_read_b32 v14, v14 offset:8704
	s_or_b64 exec, exec, s[0:1]
	v_add_u32_e32 v22, 0x9b, v22
	v_cmp_gt_u32_e32 vcc, s33, v22
	s_and_saveexec_b64 s[0:1], vcc
	v_sub_u32_e32 v15, s30, v124
	v_add_u32_e32 v15, v15, v163
	v_lshl_add_u32 v15, v15, 2, s8
	ds_read_b32 v15, v15 offset:8704
	s_or_b64 exec, exec, s[0:1]
	s_mov_b64 s[0:1], 0

; #define SA_LOAD(tbase) do { const bf16* kp_ = Kp + (size_t)((tbase) + r32) * kvpitch + 8 * hi; \
;         _Pragma("unroll") for (int ks = 0; ks < 4; ++ks) kf[ks] = *(const bf16x8*)(kp_ + 16 * ks); \
;         _Pragma("unroll") for (int e = 0; e < 4; ++e) { const int c = lane + 64 * e; vr[e] = *(const v4u*)(Vp + (size_t)((tbase) + (c >> 3)) * kvpitch + (c & 7) * 8); } } while (0)
; template <int MODE> ...
;     ...
;     const int qrow = qt + (r32 >> 4), qc = qcol0 + (r32 & 15);
;     const int qtok = MODE == 0 ? qt + r32 : qrow * 64 + qc;
;     bf16x8 qf[4];
; #pragma unroll
;     for (int ks = 0; ks < 4; ++ks) qf[ks] = *(const bf16x8*)(Qb + (size_t)qtok * qpitch + 16 * ks + 8 * hi);
;     int nt, tb0, tstep, rsA = 0, kc0 = 0, my_rs = 0, my_cs = 0;
;     if (MODE == 0) { const int t0 = qt - 128 < 0 ? 0 : qt - 128; const int t1 = qt + 160 > SEQ_ ? SEQ_ : qt + 160; tb0 = t0; nt = (t1 - t0) >> 5; tstep = 32; }
;     else { rsA = qt - 4; rsA = rsA < 0 ? 0 : (rsA > 248 ? 248 : rsA); int rsB = qt - 3; rsB = rsB < 0 ? 0 : (rsB > 248 ? 248 : rsB); nt = 8 + (rsB - rsA);
;         kc0 = qcol0 - 8; kc0 = kc0 < 0 ? 0 : (kc0 > 32 ? 32 : kc0); tb0 = rsA * 64 + kc0; tstep = 64;
;         my_rs = qrow - 4; my_rs = my_rs < 0 ? 0 : (my_rs > 248 ? 248 : my_rs); my_cs = qc - 8; my_cs = my_cs < 0 ? 0 : (my_cs > 48 ? 48 : my_cs); }
;     bf16x8 kf[4]; v4u vr[4];
;     ...
;     SA_LOAD(tb0);
;     float bmx = -1e30f;
;     for (int e = lane; e < ntab; e += 64) { const float tv_ = gtab[e] * tabscale; tab[e] = tv_; bmx = fmaxf(bmx, tv_); }
; #pragma unroll
;     for (int o_ = 1; o_ < 64; o_ <<= 1) bmx = fmaxf(bmx, __shfl_xor(bmx, o_));
; __global__ void __launch_bounds__(512) mega_fwd(Args args) {
;     ...
;                 const int u = uu & 511; const int qb = u & 63, h = (u >> 6) & 3, b = u >> 8; const size_t rb = (size_t)b * SEQ_;
;                 small_attn_wave<1>(QKV + pg8::OFF_QA + rb * 256 + h * 64, 256, QKV + pg8::OFF_KA + rb * 256 + h * 64, QKV + pg8::OFF_VA + rb * 256 + h * 64, 256,
;                                    YB + rb * 1024 + h * 64, qb * 4 + 2 * (wave >> 2), 16 * (wave & 3), args.in[I_RPB] + (size_t)(l * 4 + h) * 465, 465, LOG2E_, 0.f, GSS + (size_t)(l * 3 + 0) * MT + rb, (const unsigned*)(ws + WS_KMAX) + ((l * 2 + 0) * 4 + h) * 2, wl, lane);
.LBB0_595:
	s_bfe_u32 s37, s15, 0x20006
	v_readlane_b32 s4, v255, 14
	s_mul_i32 s0, s37, 0x1d1
	s_mul_i32 s1, s4, 0x744
	s_add_i32 s34, s1, s0
	s_lshl_b32 s0, s15, 6
	s_and_b32 s20, s0, 0x4000
	s_lshr_b32 s30, s15, 6
	s_lshl_b32 s29, s20, 9
	s_add_u32 s0, s2, s29
	s_addc_u32 s1, s3, 0
	s_lshl_b32 s21, s37, 6
	s_lshl_b32 s31, s37, 7
	v_readlane_b32 s5, v255, 15
	s_add_u32 s4, s0, s31
	s_addc_u32 s5, s1, 0
	v_readlane_b32 s0, v254, 11
	s_add_u32 s0, s0, s29
	v_readlane_b32 s1, v254, 12
	s_addc_u32 s1, s1, 0
	s_add_u32 s0, s0, s31
	s_addc_u32 s1, s1, 0
	v_readlane_b32 s12, v254, 13
	s_add_u32 s29, s12, s29
	v_readlane_b32 s12, v254, 14
	v_lshl_add_u64 v[0:1], s[34:35], 2, v[118:119]
	s_addc_u32 s34, s12, 0
	s_add_u32 s74, s29, s31
	s_addc_u32 s75, s34, 0
	s_lshl_b32 s29, s15, 2
	s_and_b32 s29, s29, 0xfc
	s_add_i32 s29, s29, s10
	v_or_b32_e32 v2, s29, v121
	v_lshl_or_b32 v116, v2, 6, v123
	v_ashrrev_i32_e32 v117, 31, v116
	v_lshlrev_b64 v[4:5], 9, v[116:117]
	v_lshl_add_u64 v[4:5], s[4:5], 0, v[4:5]
	v_lshlrev_b32_e32 v16, 1, v112
	v_mov_b32_e32 v17, v129
	v_med3_i32 v3, s29, 4, v233
	v_lshl_add_u64 v[4:5], v[4:5], 0, v[16:17]
	v_readfirstlane_b32 s31, v3
	v_add_u32_e32 v3, -4, v3
	global_load_dwordx4 v[64:67], v[4:5], off
	global_load_dwordx4 v[68:71], v[4:5], off offset:32
	global_load_dwordx4 v[72:75], v[4:5], off offset:64
	global_load_dwordx4 v[76:79], v[4:5], off offset:96
	v_lshlrev_b32_e32 v4, 6, v3
	v_add_u32_e32 v22, v155, v4
	v_add_u32_e32 v4, v22, v113
	v_mov_b32_e32 v5, v129
	v_lshlrev_b64 v[4:5], 9, v[4:5]
	v_lshl_add_u64 v[4:5], s[0:1], 0, v[4:5]
	v_lshl_add_u64 v[4:5], v[4:5], 0, v[16:17]
	global_load_dwordx4 v[80:83], v[4:5], off
	global_load_dwordx4 v[84:87], v[4:5], off offset:32
	global_load_dwordx4 v[88:91], v[4:5], off offset:64
	global_load_dwordx4 v[92:95], v[4:5], off offset:96
	v_mov_b32_e32 v115, v129
	v_or_b32_e32 v4, v22, v150
	v_mov_b32_e32 v5, v129
	v_lshl_add_u64 v[18:19], s[74:75], 0, v[114:115]
	v_lshlrev_b64 v[4:5], 9, v[4:5]
	v_lshl_add_u64 v[4:5], v[18:19], 0, v[4:5]
	global_load_dwordx4 v[96:99], v[4:5], off
	v_add_u32_e32 v4, v22, v151
	v_mov_b32_e32 v5, v129
	v_lshlrev_b64 v[4:5], 9, v[4:5]
	v_lshl_add_u64 v[4:5], v[18:19], 0, v[4:5]
	global_load_dwordx4 v[100:103], v[4:5], off
	v_add_u32_e32 v4, v22, v152
	v_mov_b32_e32 v5, v129
	v_lshlrev_b64 v[4:5], 9, v[4:5]
	v_lshl_add_u64 v[4:5], v[18:19], 0, v[4:5]
	global_load_dwordx4 v[104:107], v[4:5], off
	v_add_u32_e32 v4, v22, v153
	v_mov_b32_e32 v5, v129
	v_lshlrev_b64 v[4:5], 9, v[4:5]
	v_lshl_add_u64 v[4:5], v[18:19], 0, v[4:5]
	global_load_dwordx4 v[108:111], v[4:5], off
	v_mov_b32_e32 v4, 0xf149f2ca
	s_movk_i32 s34, 0x190
	global_load_dword v7, v[0:1], off
	global_load_dword v8, v[0:1], off offset:256
	global_load_dword v9, v[0:1], off offset:512
	global_load_dword v10, v[0:1], off offset:768
	global_load_dword v11, v[0:1], off offset:1024
	global_load_dword v12, v[0:1], off offset:1280
	global_load_dword v13, v[0:1], off offset:1536
	s_mov_b64 s[4:5], exec
	v_cmp_gt_u32_e32 vcc, 17, v133
	s_and_b64 exec, exec, vcc
	global_load_dword v14, v[0:1], off offset:1792
	s_mov_b64 exec, s[4:5]
	s_waitcnt vmcnt(0)
	v_mul_f32_e32 v7, 0x3fb8aa3b, v7
	v_mul_f32_e32 v8, 0x3fb8aa3b, v8
	v_mul_f32_e32 v9, 0x3fb8aa3b, v9
	v_mul_f32_e32 v10, 0x3fb8aa3b, v10
	v_mul_f32_e32 v11, 0x3fb8aa3b, v11
	v_mul_f32_e32 v12, 0x3fb8aa3b, v12
	v_mul_f32_e32 v13, 0x3fb8aa3b, v13
	ds_write_b32 v162, v7
	ds_write_b32 v162, v8 offset:256
	ds_write_b32 v162, v9 offset:512
	ds_write_b32 v162, v10 offset:768
	ds_write_b32 v162, v11 offset:1024
	ds_write_b32 v162, v12 offset:1280
	ds_write_b32 v162, v13 offset:1536
	v_max_f32_e32 v4, v4, v7
	v_max_f32_e32 v4, v4, v8
	v_max_f32_e32 v4, v4, v9
	v_max_f32_e32 v4, v4, v10
	v_max_f32_e32 v4, v4, v11
	v_max_f32_e32 v4, v4, v12
	v_max_f32_e32 v4, v4, v13
	s_and_b64 exec, exec, vcc
	v_mul_f32_e32 v14, 0x3fb8aa3b, v14
	ds_write_b32 v162, v14 offset:1792
	v_max_f32_e32 v4, v4, v14
	s_mov_b64 exec, s[4:5]
	s_lshl_b32 s4, s37, 1
	s_or_b32 s34, s4, s9
	s_lshl_b64 s[4:5], s[34:35], 2
	ds_bpermute_b32 v1, v156, v4
	s_add_u32 s74, s76, s4
	s_addc_u32 s75, s77, s5
	global_load_dwordx2 v[20:21], v129, s[74:75]
	v_max_f32_e32 v4, v4, v4
	s_waitcnt lgkmcnt(0)
	v_max_f32_e32 v1, v1, v1
	v_max_f32_e32 v1, v4, v1
	ds_bpermute_b32 v4, v157, v1
	v_and_b32_e32 v5, 0xffff0000, v65
	v_mul_f32_e32 v5, v5, v5
	v_med3_i32 v0, v2, 4, v233
	v_sub_u32_e32 v0, s31, v0
	s_waitcnt lgkmcnt(0)
	v_max_f32_e32 v4, v4, v4
	v_max_f32_e32 v1, v1, v4
	ds_bpermute_b32 v4, v158, v1
	v_cmp_gt_u32_e32 vcc, 8, v0
	v_sub_u32_e32 v0, v3, v2
	s_and_b64 s[74:75], vcc, s[38:39]
	ds_write_b128 v186, v[96:99]
	ds_write_b128 v186, v[100:103] offset:1152
	ds_write_b128 v186, v[104:107] offset:2304
	ds_write_b128 v186, v[108:111] offset:3456
	s_waitcnt lgkmcnt(4)
	v_max_f32_e32 v4, v4, v4
	v_max_f32_e32 v1, v1, v4
	ds_bpermute_b32 v4, v159, v1
	s_waitcnt lgkmcnt(0)
	v_max_f32_e32 v4, v4, v4
	v_max_f32_e32 v1, v1, v4
	ds_bpermute_b32 v4, v160, v1
	s_waitcnt lgkmcnt(0)
; #define LAS __attribute__((address_space(3)))
; #define SA_LOAD(tbase) do { const bf16* kp_ = Kp + (size_t)((tbase) + r32) * kvpitch + 8 * hi; \
;         _Pragma("unroll") for (int ks = 0; ks < 4; ++ks) kf[ks] = *(const bf16x8*)(kp_ + 16 * ks); \
;         _Pragma("unroll") for (int e = 0; e < 4; ++e) { const int c = lane + 64 * e; vr[e] = *(const v4u*)(Vp + (size_t)((tbase) + (c >> 3)) * kvpitch + (c & 7) * 8); } } while (0)
; #define SA_VWRITE(buf) do { _Pragma("unroll") for (int e = 0; e < 4; ++e) { const int c = lane + 64 * e; *(LAS v4u*)(wl + (buf) * 4608 + (c >> 3) * 144 + (c & 7) * 16) = vr[e]; } } while (0)
; #define SA_QK(X) do { _Pragma("unroll") for (int ks = 0; ks < 4; ++ks) X = __builtin_amdgcn_mfma_f32_32x32x16_bf16(kf[ks], qf[ks], X, 0, 0, 0); } while (0)
; template <int MODE> ...
;     ...
;     SA_LOAD(tb0);
;     float bmx = -1e30f;
;     for (int e = lane; e < ntab; e += 64) { const float tv_ = gtab[e] * tabscale; tab[e] = tv_; bmx = fmaxf(bmx, tv_); }
; #pragma unroll
;     for (int o_ = 1; o_ < 64; o_ <<= 1) bmx = fmaxf(bmx, __shfl_xor(bmx, o_));
;     float ref;
;     { float qs = 0.f;
; #pragma unroll
;       for (int ks = 0; ks < 4; ++ks) { const v4u qw = __builtin_bit_cast(v4u, qf[ks]);
; #pragma unroll
;           for (int e = 0; e < 4; ++e) { const float lo_ = __uint_as_float(qw[e] << 16), hi_ = __uint_as_float(qw[e] & 0xffff0000u); qs += lo_ * lo_ + hi_ * hi_; } }
;       auto rr = __builtin_amdgcn_permlane32_swap(__float_as_uint(qs), __float_as_uint(qs), false, false); qs = __uint_as_float(rr[0]) + __uint_as_float(rr[1]);
;       const float k2 = __uint_as_float(kmax2[0]) + __uint_as_float(kmax2[1]);
;       ref = fminf(__builtin_sqrtf(qs * k2) * 1.03f + bmx, 110.0f); }
;     f32x16 o0 = {}, o1 = {};
;     float lsum = 0.f;
;     const int i16 = lane & 15, g16 = (lane >> 4) & 1;
;     LAS unsigned char* vaddr = wl + (4 * hi + (i16 >> 2)) * 144 + g16 * 32 + 8 * (i16 & 3);
;     f32x16 xa_, xb_;
;     SA_VWRITE(0); SA_CINIT(0, xa_); SA_QK(xa_);
;     if (nt > 1) SA_LOAD(tb0 + tstep);
	v_max_f32_e32 v4, v4, v4
	v_max_f32_e32 v23, v1, v4
	v_and_b32_e32 v4, 0xffff0000, v64
	v_lshlrev_b32_e32 v1, 16, v64
	v_mul_f32_e32 v4, v4, v4
	v_fmac_f32_e32 v4, v1, v1
	v_lshlrev_b32_e32 v1, 16, v65
	v_fmac_f32_e32 v5, v1, v1
	v_add_f32_e32 v1, v4, v5
	v_and_b32_e32 v5, 0xffff0000, v66
	v_lshlrev_b32_e32 v4, 16, v66
	v_mul_f32_e32 v5, v5, v5
	v_fmac_f32_e32 v5, v4, v4
	v_add_f32_e32 v1, v5, v1
	v_and_b32_e32 v5, 0xffff0000, v67
	v_lshlrev_b32_e32 v4, 16, v67
	v_mul_f32_e32 v5, v5, v5
	v_fmac_f32_e32 v5, v4, v4
	v_add_f32_e32 v1, v5, v1
	v_and_b32_e32 v5, 0xffff0000, v68
	v_lshlrev_b32_e32 v4, 16, v68
	v_mul_f32_e32 v5, v5, v5
	v_fmac_f32_e32 v5, v4, v4
	v_add_f32_e32 v1, v5, v1
	v_and_b32_e32 v5, 0xffff0000, v69
	v_lshlrev_b32_e32 v4, 16, v69
	v_mul_f32_e32 v5, v5, v5
	v_fmac_f32_e32 v5, v4, v4
	v_add_f32_e32 v1, v5, v1
	v_and_b32_e32 v5, 0xffff0000, v70
	v_lshlrev_b32_e32 v4, 16, v70
	v_mul_f32_e32 v5, v5, v5
	v_fmac_f32_e32 v5, v4, v4
	v_add_f32_e32 v1, v5, v1
	v_and_b32_e32 v5, 0xffff0000, v71
	v_lshlrev_b32_e32 v4, 16, v71
	v_mul_f32_e32 v5, v5, v5
	v_fmac_f32_e32 v5, v4, v4
	v_add_f32_e32 v1, v5, v1
	v_and_b32_e32 v5, 0xffff0000, v72
	v_lshlrev_b32_e32 v4, 16, v72
	v_mul_f32_e32 v5, v5, v5
	v_fmac_f32_e32 v5, v4, v4
	v_add_f32_e32 v1, v5, v1
	v_and_b32_e32 v5, 0xffff0000, v73
	v_lshlrev_b32_e32 v4, 16, v73
	v_mul_f32_e32 v5, v5, v5
	v_fmac_f32_e32 v5, v4, v4
	v_add_f32_e32 v1, v5, v1
	v_and_b32_e32 v5, 0xffff0000, v74
	v_lshlrev_b32_e32 v4, 16, v74
	v_mul_f32_e32 v5, v5, v5
	v_fmac_f32_e32 v5, v4, v4
	v_add_f32_e32 v1, v5, v1
	v_and_b32_e32 v5, 0xffff0000, v75
	v_lshlrev_b32_e32 v4, 16, v75
	v_mul_f32_e32 v5, v5, v5
	v_fmac_f32_e32 v5, v4, v4
	v_add_f32_e32 v1, v5, v1
	v_and_b32_e32 v5, 0xffff0000, v76
	v_lshlrev_b32_e32 v4, 16, v76
	v_mul_f32_e32 v5, v5, v5
	v_fmac_f32_e32 v5, v4, v4
	v_add_f32_e32 v1, v5, v1
	v_and_b32_e32 v5, 0xffff0000, v77
	v_lshlrev_b32_e32 v4, 16, v77
	v_mul_f32_e32 v5, v5, v5
	v_fmac_f32_e32 v5, v4, v4
	v_add_f32_e32 v1, v5, v1
	v_and_b32_e32 v5, 0xffff0000, v78
	v_lshlrev_b32_e32 v4, 16, v78
	v_mul_f32_e32 v5, v5, v5
	v_fmac_f32_e32 v5, v4, v4
	v_add_f32_e32 v1, v5, v1
	v_and_b32_e32 v5, 0xffff0000, v79
	ds_bpermute_b32 v24, v161, v23
	v_lshlrev_b32_e32 v4, 16, v79
	v_mul_f32_e32 v5, v5, v5
	v_fmac_f32_e32 v5, v4, v4
	v_add_f32_e32 v25, v5, v1
	v_mad_u64_u32 v[0:1], s[4:5], v0, 31, v[120:121]
	v_mov_b32_e32 v26, v25
	v_cndmask_b32_e32 v0, 0, v0, vcc
	s_nop 0
	v_permlane32_swap_b32_e32 v25, v26
	v_lshl_add_u32 v17, v0, 2, s8
	v_mov_b32_e32 v1, 0xf149f2ca
	v_mov_b32_e32 v0, 0xf149f2ca
	s_and_saveexec_b64 s[4:5], s[74:75]
	ds_read_b32 v0, v17 offset:9216
	s_or_b64 exec, exec, s[4:5]
	s_and_b64 s[74:75], vcc, s[40:41]
	s_and_saveexec_b64 s[4:5], s[74:75]
	ds_read_b32 v1, v17 offset:9220
	s_or_b64 exec, exec, s[4:5]
	s_and_b64 s[74:75], vcc, s[42:43]
	v_mov_b32_e32 v3, 0xf149f2ca
	v_mov_b32_e32 v2, 0xf149f2ca
	s_and_saveexec_b64 s[4:5], s[74:75]
	ds_read_b32 v2, v17 offset:9224
	s_or_b64 exec, exec, s[4:5]
	s_and_b64 s[74:75], vcc, s[44:45]
	s_and_saveexec_b64 s[4:5], s[74:75]
	ds_read_b32 v3, v17 offset:9228
	s_or_b64 exec, exec, s[4:5]
	s_and_b64 s[74:75], vcc, s[46:47]
	v_mov_b32_e32 v5, 0xf149f2ca
	v_mov_b32_e32 v4, 0xf149f2ca
	s_and_saveexec_b64 s[4:5], s[74:75]
	ds_read_b32 v4, v17 offset:9248
	s_or_b64 exec, exec, s[4:5]
	s_and_b64 s[74:75], vcc, s[48:49]
	s_and_saveexec_b64 s[4:5], s[74:75]
	ds_read_b32 v5, v17 offset:9252
	s_or_b64 exec, exec, s[4:5]
	s_and_b64 s[74:75], vcc, s[50:51]
	v_mov_b32_e32 v7, 0xf149f2ca
	v_mov_b32_e32 v6, 0xf149f2ca
	s_and_saveexec_b64 s[4:5], s[74:75]
	ds_read_b32 v6, v17 offset:9256
	s_or_b64 exec, exec, s[4:5]
	s_and_b64 s[74:75], vcc, s[52:53]
	s_and_saveexec_b64 s[4:5], s[74:75]
	ds_read_b32 v7, v17 offset:9260
	s_or_b64 exec, exec, s[4:5]
	s_and_b64 s[74:75], vcc, s[54:55]
	v_mov_b32_e32 v9, 0xf149f2ca
	v_mov_b32_e32 v8, 0xf149f2ca
	s_and_saveexec_b64 s[4:5], s[74:75]
	ds_read_b32 v8, v17 offset:9280
	s_or_b64 exec, exec, s[4:5]
	s_and_b64 s[74:75], vcc, s[56:57]
	s_and_saveexec_b64 s[4:5], s[74:75]
	ds_read_b32 v9, v17 offset:9284
	s_or_b64 exec, exec, s[4:5]
	s_and_b64 s[74:75], vcc, s[58:59]
	v_mov_b32_e32 v11, 0xf149f2ca
	v_mov_b32_e32 v10, 0xf149f2ca
	s_and_saveexec_b64 s[4:5], s[74:75]
	ds_read_b32 v10, v17 offset:9288
	s_or_b64 exec, exec, s[4:5]
	s_and_b64 s[74:75], vcc, s[60:61]
	s_and_saveexec_b64 s[4:5], s[74:75]
	ds_read_b32 v11, v17 offset:9292
	s_or_b64 exec, exec, s[4:5]
	s_and_b64 s[74:75], vcc, s[62:63]
	v_mov_b32_e32 v13, 0xf149f2ca
	v_mov_b32_e32 v12, 0xf149f2ca
	s_and_saveexec_b64 s[4:5], s[74:75]
	ds_read_b32 v12, v17 offset:9312
	s_or_b64 exec, exec, s[4:5]
	s_and_b64 s[74:75], vcc, s[64:65]
	s_and_saveexec_b64 s[4:5], s[74:75]
	ds_read_b32 v13, v17 offset:9316
	s_or_b64 exec, exec, s[4:5]
	s_and_b64 s[74:75], vcc, s[66:67]
	v_mov_b32_e32 v15, 0xf149f2ca
	v_mov_b32_e32 v14, 0xf149f2ca
	s_and_saveexec_b64 s[4:5], s[74:75]
	ds_read_b32 v14, v17 offset:9320
	s_or_b64 exec, exec, s[4:5]
	s_and_b64 s[74:75], vcc, s[68:69]
	s_and_saveexec_b64 s[4:5], s[74:75]
	ds_read_b32 v15, v17 offset:9324
	s_or_b64 exec, exec, s[4:5]
	s_waitcnt lgkmcnt(0)
	v_mfma_f32_32x32x16_bf16 v[0:15], v[80:83], v[64:67], v[0:15]
	v_med3_i32 v17, s29, 3, v234
	s_nop 0
	v_readfirstlane_b32 s4, v17
	s_sub_i32 s31, s4, s31
	s_cmp_lt_i32 s31, -7
	v_mfma_f32_32x32x16_bf16 v[0:15], v[84:87], v[68:71], v[0:15]
	v_mfma_f32_32x32x16_bf16 v[0:15], v[88:91], v[72:75], v[0:15]
	v_mfma_f32_32x32x16_bf16 v[0:15], v[92:95], v[76:79], v[0:15]
	s_cbranch_scc1 .LBB0_631
	v_add_u32_e32 v22, 64, v22
	v_add_u32_e32 v28, v22, v113
	v_mov_b32_e32 v29, v129
	v_lshlrev_b64 v[28:29], 9, v[28:29]
	v_lshl_add_u64 v[28:29], s[0:1], 0, v[28:29]
	v_mov_b32_e32 v17, v129
	v_lshl_add_u64 v[16:17], v[28:29], 0, v[16:17]
	global_load_dwordx4 v[80:83], v[16:17], off
	global_load_dwordx4 v[84:87], v[16:17], off offset:32
	global_load_dwordx4 v[88:91], v[16:17], off offset:64
	global_load_dwordx4 v[92:95], v[16:17], off offset:96
	v_or_b32_e32 v16, v22, v150
	v_mov_b32_e32 v17, v129
	v_lshlrev_b64 v[16:17], 9, v[16:17]
	v_add_u32_e32 v28, v22, v151
	v_mov_b32_e32 v29, v129
	v_lshl_add_u64 v[16:17], v[18:19], 0, v[16:17]
	v_lshlrev_b64 v[28:29], 9, v[28:29]
	v_lshl_add_u64 v[28:29], v[18:19], 0, v[28:29]
	global_load_dwordx4 v[96:99], v[16:17], off
	global_load_dwordx4 v[100:103], v[28:29], off
	v_add_u32_e32 v16, v22, v152
	v_mov_b32_e32 v17, v129
	v_lshlrev_b64 v[16:17], 9, v[16:17]
	v_add_u32_e32 v28, v22, v153
	v_mov_b32_e32 v29, v129
	v_lshl_add_u64 v[16:17], v[18:19], 0, v[16:17]
	v_lshlrev_b64 v[28:29], 9, v[28:29]
	v_lshl_add_u64 v[18:19], v[18:19], 0, v[28:29]
	global_load_dwordx4 v[104:107], v[16:17], off
	global_load_dwordx4 v[108:111], v[18:19], off
